# scan ISSUE: global loads use SGPR base + 32-bit VGPR offset (saves 6 64-bit adds per issue)
# baseline (speedup 1.0000x reference)
.Lsx0_d:
	s_setprio 3
	s_waitcnt lgkmcnt(0)
	s_nop 6
	v_fmac_f32_dpp v30, v30, v80 row_newbcast:0 row_mask:0xf bank_mask:0xf
	v_fmac_f32_dpp v31, v31, v80 row_newbcast:0 row_mask:0xf bank_mask:0xf
	v_fmac_f32_dpp v32, v32, v80 row_newbcast:0 row_mask:0xf bank_mask:0xf
	v_fmac_f32_dpp v33, v33, v80 row_newbcast:0 row_mask:0xf bank_mask:0xf
	v_fmac_f32_dpp v30, v30, v81 row_newbcast:1 row_mask:0xf bank_mask:0xf
	v_fmac_f32_dpp v31, v31, v81 row_newbcast:1 row_mask:0xf bank_mask:0xf
	v_fmac_f32_dpp v32, v32, v81 row_newbcast:1 row_mask:0xf bank_mask:0xf
	v_fmac_f32_dpp v33, v33, v81 row_newbcast:1 row_mask:0xf bank_mask:0xf
	v_fmac_f32_dpp v30, v30, v82 row_newbcast:2 row_mask:0xf bank_mask:0xf
	v_fmac_f32_dpp v31, v31, v82 row_newbcast:2 row_mask:0xf bank_mask:0xf
	v_fmac_f32_dpp v32, v32, v82 row_newbcast:2 row_mask:0xf bank_mask:0xf
	v_fmac_f32_dpp v33, v33, v82 row_newbcast:2 row_mask:0xf bank_mask:0xf
	v_fmac_f32_dpp v30, v30, v83 row_newbcast:3 row_mask:0xf bank_mask:0xf
	v_fmac_f32_dpp v31, v31, v83 row_newbcast:3 row_mask:0xf bank_mask:0xf
	v_fmac_f32_dpp v32, v32, v83 row_newbcast:3 row_mask:0xf bank_mask:0xf
	v_fmac_f32_dpp v33, v33, v83 row_newbcast:3 row_mask:0xf bank_mask:0xf
	v_fmac_f32_dpp v30, v30, v84 row_newbcast:4 row_mask:0xf bank_mask:0xf
	v_fmac_f32_dpp v31, v31, v84 row_newbcast:4 row_mask:0xf bank_mask:0xf
	v_fmac_f32_dpp v32, v32, v84 row_newbcast:4 row_mask:0xf bank_mask:0xf
	v_fmac_f32_dpp v33, v33, v84 row_newbcast:4 row_mask:0xf bank_mask:0xf
	v_fmac_f32_dpp v30, v30, v85 row_newbcast:5 row_mask:0xf bank_mask:0xf
	v_fmac_f32_dpp v31, v31, v85 row_newbcast:5 row_mask:0xf bank_mask:0xf
	v_fmac_f32_dpp v32, v32, v85 row_newbcast:5 row_mask:0xf bank_mask:0xf
	v_fmac_f32_dpp v33, v33, v85 row_newbcast:5 row_mask:0xf bank_mask:0xf
	v_fmac_f32_dpp v30, v30, v86 row_newbcast:6 row_mask:0xf bank_mask:0xf
	v_fmac_f32_dpp v31, v31, v86 row_newbcast:6 row_mask:0xf bank_mask:0xf
	v_fmac_f32_dpp v32, v32, v86 row_newbcast:6 row_mask:0xf bank_mask:0xf
	v_fmac_f32_dpp v33, v33, v86 row_newbcast:6 row_mask:0xf bank_mask:0xf
	v_fmac_f32_dpp v30, v30, v87 row_newbcast:7 row_mask:0xf bank_mask:0xf
	v_fmac_f32_dpp v31, v31, v87 row_newbcast:7 row_mask:0xf bank_mask:0xf
	v_fmac_f32_dpp v32, v32, v87 row_newbcast:7 row_mask:0xf bank_mask:0xf
	v_fmac_f32_dpp v33, v33, v87 row_newbcast:7 row_mask:0xf bank_mask:0xf
	v_fmac_f32_dpp v30, v30, v88 row_newbcast:8 row_mask:0xf bank_mask:0xf
	v_fmac_f32_dpp v31, v31, v88 row_newbcast:8 row_mask:0xf bank_mask:0xf
	v_fmac_f32_dpp v32, v32, v88 row_newbcast:8 row_mask:0xf bank_mask:0xf
	v_fmac_f32_dpp v33, v33, v88 row_newbcast:8 row_mask:0xf bank_mask:0xf
	v_fmac_f32_dpp v30, v30, v89 row_newbcast:9 row_mask:0xf bank_mask:0xf
	v_fmac_f32_dpp v31, v31, v89 row_newbcast:9 row_mask:0xf bank_mask:0xf
	v_fmac_f32_dpp v32, v32, v89 row_newbcast:9 row_mask:0xf bank_mask:0xf
	v_fmac_f32_dpp v33, v33, v89 row_newbcast:9 row_mask:0xf bank_mask:0xf
	v_fmac_f32_dpp v30, v30, v90 row_newbcast:10 row_mask:0xf bank_mask:0xf
	v_fmac_f32_dpp v31, v31, v90 row_newbcast:10 row_mask:0xf bank_mask:0xf
	v_fmac_f32_dpp v32, v32, v90 row_newbcast:10 row_mask:0xf bank_mask:0xf
	v_fmac_f32_dpp v33, v33, v90 row_newbcast:10 row_mask:0xf bank_mask:0xf
	v_fmac_f32_dpp v30, v30, v91 row_newbcast:11 row_mask:0xf bank_mask:0xf
	v_fmac_f32_dpp v31, v31, v91 row_newbcast:11 row_mask:0xf bank_mask:0xf
	v_fmac_f32_dpp v32, v32, v91 row_newbcast:11 row_mask:0xf bank_mask:0xf
	v_fmac_f32_dpp v33, v33, v91 row_newbcast:11 row_mask:0xf bank_mask:0xf
	v_fmac_f32_dpp v30, v30, v92 row_newbcast:12 row_mask:0xf bank_mask:0xf
	v_fmac_f32_dpp v31, v31, v92 row_newbcast:12 row_mask:0xf bank_mask:0xf
	v_fmac_f32_dpp v32, v32, v92 row_newbcast:12 row_mask:0xf bank_mask:0xf
	v_fmac_f32_dpp v33, v33, v92 row_newbcast:12 row_mask:0xf bank_mask:0xf
	v_fmac_f32_dpp v30, v30, v93 row_newbcast:13 row_mask:0xf bank_mask:0xf
	v_fmac_f32_dpp v31, v31, v93 row_newbcast:13 row_mask:0xf bank_mask:0xf
	v_fmac_f32_dpp v32, v32, v93 row_newbcast:13 row_mask:0xf bank_mask:0xf
	v_fmac_f32_dpp v33, v33, v93 row_newbcast:13 row_mask:0xf bank_mask:0xf
	v_fmac_f32_dpp v30, v30, v94 row_newbcast:14 row_mask:0xf bank_mask:0xf
	v_fmac_f32_dpp v31, v31, v94 row_newbcast:14 row_mask:0xf bank_mask:0xf
	v_fmac_f32_dpp v32, v32, v94 row_newbcast:14 row_mask:0xf bank_mask:0xf
	v_fmac_f32_dpp v33, v33, v94 row_newbcast:14 row_mask:0xf bank_mask:0xf
	v_lshrrev_b32_e32 v82, 6, v198
	v_mul_u32_u24_e32 v82, 0x500, v82
	v_mad_u32_u24 v82, v145, 20, v82
	v_and_b32_e32 v83, 15, v198
	v_lshl_add_u32 v82, v83, 1, v82
	v_add_u32_e32 v82, 0x10a00, v82
	v_cvt_pk_bf16_f32 v80, v30, v31
	v_cvt_pk_bf16_f32 v81, v32, v33
	ds_write_b16 v82, v80 offset:0
	ds_write_b16_d16_hi v82, v80 offset:80
	ds_write_b16 v82, v81 offset:160
	ds_write_b16_d16_hi v82, v81 offset:240
	s_setprio 1

.Lcp0:
	s_cmp_eq_u32 s36, 0
	s_cbranch_scc1 .Lis0b
	s_cmp_gt_u32 s36, 62
	s_cbranch_scc1 .Lis0b
	s_add_i32 s24, s19, 0xffffffc0
	s_add_i32 s25, s21, 0x30
	s_and_b64 s[98:99], s[12:13], exec
	s_cselect_b32 s24, s25, s24
	v_lshl_add_u32 v194, s24, 6, v183
	v_lshlrev_b32_e32 v112, 1, v194
	global_load_dword v5, v112, s[44:45]
	global_load_dword v6, v112, s[42:43]
	global_load_dword v7, v112, s[0:1]
	global_load_dword v8, v112, s[34:35]
	global_load_dword v9, v112, s[76:77]
	v_add_u32_e32 v194, s24, v184
	v_lshlrev_b32_e32 v114, 2, v194
	global_load_dword v110, v114, s[40:41]

.Lsx1_c:
	s_or_b64 exec, exec, s[74:75]
	v_mov_b32_e32 v22, 0
	v_mov_b32_e32 v23, 0
	v_mov_b32_e32 v24, 0
	v_mov_b32_e32 v25, 0
	s_and_saveexec_b64 s[74:75], s[56:57]
	s_cbranch_execz .LBB0_432
	ds_read_b128 v[48:51], v174
	ds_read_b128 v[60:63], v192 offset:51456
	ds_read_b128 v[52:55], v174 offset:64
	ds_read_b128 v[64:67], v192 offset:51520
	ds_read_b128 v[56:59], v175 offset:5120
	ds_read_b128 v[68:71], v199
	ds_read_b128 v[72:75], v192 offset:60672
	ds_read_b128 v[76:79], v192 offset:60736
	ds_read_b128 v[80:83], v151
	ds_read_b128 v[84:87], v151 offset:16
	ds_read_b128 v[88:91], v151 offset:32
	ds_read_b128 v[92:95], v151 offset:48
	s_waitcnt lgkmcnt(10)
	v_mfma_f32_16x16x32_bf16 v[30:33], v[48:51], v[60:63], 0
	s_waitcnt lgkmcnt(8)
	v_mfma_f32_16x16x32_bf16 v[30:33], v[52:55], v[64:67], v[30:33]
	s_waitcnt lgkmcnt(6)
	v_mfma_f32_16x16x32_bf16 v[30:33], v[56:59], v[68:71], v[30:33]
	s_waitcnt lgkmcnt(5)
	v_mfma_f32_16x16x32_bf16 v[22:25], v[48:51], v[72:75], 0
	s_waitcnt lgkmcnt(4)
	v_mfma_f32_16x16x32_bf16 v[22:25], v[52:55], v[76:79], v[22:25]
	v_cvt_pk_bf16_f32 v240, v236, v237
	global_store_dword v[238:239], v240, off
	s_setprio 3
	s_waitcnt lgkmcnt(0)
	s_nop 6
	v_fmac_f32_dpp v30, v30, v80 row_newbcast:0 row_mask:0xf bank_mask:0xf
	v_fmac_f32_dpp v31, v31, v80 row_newbcast:0 row_mask:0xf bank_mask:0xf
	v_fmac_f32_dpp v32, v32, v80 row_newbcast:0 row_mask:0xf bank_mask:0xf
	v_fmac_f32_dpp v33, v33, v80 row_newbcast:0 row_mask:0xf bank_mask:0xf
	v_fmac_f32_dpp v30, v30, v81 row_newbcast:1 row_mask:0xf bank_mask:0xf
	v_fmac_f32_dpp v31, v31, v81 row_newbcast:1 row_mask:0xf bank_mask:0xf
	v_fmac_f32_dpp v32, v32, v81 row_newbcast:1 row_mask:0xf bank_mask:0xf
	v_fmac_f32_dpp v33, v33, v81 row_newbcast:1 row_mask:0xf bank_mask:0xf
	v_fmac_f32_dpp v30, v30, v82 row_newbcast:2 row_mask:0xf bank_mask:0xf
	v_fmac_f32_dpp v31, v31, v82 row_newbcast:2 row_mask:0xf bank_mask:0xf
	v_fmac_f32_dpp v32, v32, v82 row_newbcast:2 row_mask:0xf bank_mask:0xf
	v_fmac_f32_dpp v33, v33, v82 row_newbcast:2 row_mask:0xf bank_mask:0xf
	v_fmac_f32_dpp v30, v30, v83 row_newbcast:3 row_mask:0xf bank_mask:0xf
	v_fmac_f32_dpp v31, v31, v83 row_newbcast:3 row_mask:0xf bank_mask:0xf
	v_fmac_f32_dpp v32, v32, v83 row_newbcast:3 row_mask:0xf bank_mask:0xf
	v_fmac_f32_dpp v33, v33, v83 row_newbcast:3 row_mask:0xf bank_mask:0xf
	v_fmac_f32_dpp v30, v30, v84 row_newbcast:4 row_mask:0xf bank_mask:0xf
	v_fmac_f32_dpp v31, v31, v84 row_newbcast:4 row_mask:0xf bank_mask:0xf
	v_fmac_f32_dpp v32, v32, v84 row_newbcast:4 row_mask:0xf bank_mask:0xf
	v_fmac_f32_dpp v33, v33, v84 row_newbcast:4 row_mask:0xf bank_mask:0xf
	v_fmac_f32_dpp v30, v30, v85 row_newbcast:5 row_mask:0xf bank_mask:0xf
	v_fmac_f32_dpp v31, v31, v85 row_newbcast:5 row_mask:0xf bank_mask:0xf
	v_fmac_f32_dpp v32, v32, v85 row_newbcast:5 row_mask:0xf bank_mask:0xf
	v_fmac_f32_dpp v33, v33, v85 row_newbcast:5 row_mask:0xf bank_mask:0xf
	v_fmac_f32_dpp v30, v30, v86 row_newbcast:6 row_mask:0xf bank_mask:0xf
	v_fmac_f32_dpp v31, v31, v86 row_newbcast:6 row_mask:0xf bank_mask:0xf
	v_fmac_f32_dpp v32, v32, v86 row_newbcast:6 row_mask:0xf bank_mask:0xf
	v_fmac_f32_dpp v33, v33, v86 row_newbcast:6 row_mask:0xf bank_mask:0xf
	v_fmac_f32_dpp v30, v30, v87 row_newbcast:7 row_mask:0xf bank_mask:0xf
	v_fmac_f32_dpp v31, v31, v87 row_newbcast:7 row_mask:0xf bank_mask:0xf
	v_fmac_f32_dpp v32, v32, v87 row_newbcast:7 row_mask:0xf bank_mask:0xf
	v_fmac_f32_dpp v33, v33, v87 row_newbcast:7 row_mask:0xf bank_mask:0xf
	v_fmac_f32_dpp v30, v30, v88 row_newbcast:8 row_mask:0xf bank_mask:0xf
	v_fmac_f32_dpp v31, v31, v88 row_newbcast:8 row_mask:0xf bank_mask:0xf
	v_fmac_f32_dpp v32, v32, v88 row_newbcast:8 row_mask:0xf bank_mask:0xf
	v_fmac_f32_dpp v33, v33, v88 row_newbcast:8 row_mask:0xf bank_mask:0xf
	v_fmac_f32_dpp v30, v30, v89 row_newbcast:9 row_mask:0xf bank_mask:0xf
	v_fmac_f32_dpp v31, v31, v89 row_newbcast:9 row_mask:0xf bank_mask:0xf
	v_fmac_f32_dpp v32, v32, v89 row_newbcast:9 row_mask:0xf bank_mask:0xf
	v_fmac_f32_dpp v33, v33, v89 row_newbcast:9 row_mask:0xf bank_mask:0xf
	v_fmac_f32_dpp v30, v30, v90 row_newbcast:10 row_mask:0xf bank_mask:0xf
	v_fmac_f32_dpp v31, v31, v90 row_newbcast:10 row_mask:0xf bank_mask:0xf
	v_fmac_f32_dpp v32, v32, v90 row_newbcast:10 row_mask:0xf bank_mask:0xf
	v_fmac_f32_dpp v33, v33, v90 row_newbcast:10 row_mask:0xf bank_mask:0xf
	v_fmac_f32_dpp v30, v30, v91 row_newbcast:11 row_mask:0xf bank_mask:0xf
	v_fmac_f32_dpp v31, v31, v91 row_newbcast:11 row_mask:0xf bank_mask:0xf
	v_fmac_f32_dpp v32, v32, v91 row_newbcast:11 row_mask:0xf bank_mask:0xf
	v_fmac_f32_dpp v33, v33, v91 row_newbcast:11 row_mask:0xf bank_mask:0xf
	v_fmac_f32_dpp v30, v30, v92 row_newbcast:12 row_mask:0xf bank_mask:0xf
	v_fmac_f32_dpp v31, v31, v92 row_newbcast:12 row_mask:0xf bank_mask:0xf
	v_fmac_f32_dpp v32, v32, v92 row_newbcast:12 row_mask:0xf bank_mask:0xf
	v_fmac_f32_dpp v33, v33, v92 row_newbcast:12 row_mask:0xf bank_mask:0xf
	v_fmac_f32_dpp v30, v30, v93 row_newbcast:13 row_mask:0xf bank_mask:0xf
	v_fmac_f32_dpp v31, v31, v93 row_newbcast:13 row_mask:0xf bank_mask:0xf
	v_fmac_f32_dpp v32, v32, v93 row_newbcast:13 row_mask:0xf bank_mask:0xf
	v_fmac_f32_dpp v33, v33, v93 row_newbcast:13 row_mask:0xf bank_mask:0xf
	v_fmac_f32_dpp v30, v30, v94 row_newbcast:14 row_mask:0xf bank_mask:0xf
	v_fmac_f32_dpp v31, v31, v94 row_newbcast:14 row_mask:0xf bank_mask:0xf
	v_fmac_f32_dpp v32, v32, v94 row_newbcast:14 row_mask:0xf bank_mask:0xf
	v_fmac_f32_dpp v33, v33, v94 row_newbcast:14 row_mask:0xf bank_mask:0xf
	v_lshrrev_b32_e32 v82, 6, v198
	v_mul_u32_u24_e32 v82, 0x500, v82
	v_mad_u32_u24 v82, v145, 20, v82
	v_and_b32_e32 v83, 15, v198
	v_lshl_add_u32 v82, v83, 1, v82
	v_add_u32_e32 v82, 0x10a00, v82
	v_cvt_pk_bf16_f32 v80, v30, v31
	v_cvt_pk_bf16_f32 v81, v32, v33
	ds_write_b16 v82, v80 offset:5120
	ds_write_b16_d16_hi v82, v80 offset:5200
	ds_write_b16 v82, v81 offset:5280
	ds_write_b16_d16_hi v82, v81 offset:5360
	s_setprio 1

.Lcp1:
	s_cmp_gt_u32 s36, 61
	s_cbranch_scc1 .Lis1bw
	s_add_i32 s24, s19, 0xffffffb0
	s_add_i32 s25, s21, 64
	s_and_b64 s[98:99], s[12:13], exec
	s_cselect_b32 s24, s25, s24
	v_lshl_add_u32 v194, s24, 6, v183
	v_lshlrev_b32_e32 v112, 1, v194
	global_load_dword v0, v112, s[44:45]
	global_load_dword v1, v112, s[42:43]
	global_load_dword v2, v112, s[0:1]
	global_load_dword v4, v112, s[76:77]
	global_load_dword v3, v112, s[34:35]
	v_add_u32_e32 v194, s24, v184
	v_lshlrev_b32_e32 v114, 2, v194
	global_load_dword v108, v114, s[40:41]
	s_branch .Lis1b
